# adds: attention row-max via v_permlane16/32_swap instead of two ds_bpermute round trips
# speedup vs baseline: 1.0017x; 1.0017x over previous
.LBB0_413:
	v_mov_b32_e32 v140, v243
	v_mov_b32_e32 v141, v243
	s_nop 1
	v_permlane16_swap_b32_e32 v140, v141
	v_max_f32_e32 v140, v140, v141
	v_mov_b32_e32 v141, v140
	s_nop 1
	v_permlane32_swap_b32_e32 v140, v141
	v_max3_f32 v242, v241, v140, v141
	v_cmp_neq_f32_e32 vcc, v242, v241
	s_cbranch_vccz .LBB0_415
	v_sub_f32_e32 v140, v241, v242
	v_exp_f32_e32 v140, v140
	s_nop 0
	v_pk_mul_f32 v[130:131], v[130:131], v[140:141] op_sel_hi:[1,0]
	v_pk_mul_f32 v[128:129], v[128:129], v[140:141] op_sel_hi:[1,0]
	v_pk_mul_f32 v[126:127], v[126:127], v[140:141] op_sel_hi:[1,0]
	v_pk_mul_f32 v[124:125], v[124:125], v[140:141] op_sel_hi:[1,0]
	v_pk_mul_f32 v[122:123], v[122:123], v[140:141] op_sel_hi:[1,0]
	v_pk_mul_f32 v[120:121], v[120:121], v[140:141] op_sel_hi:[1,0]
	v_pk_mul_f32 v[118:119], v[118:119], v[140:141] op_sel_hi:[1,0]
	v_pk_mul_f32 v[116:117], v[116:117], v[140:141] op_sel_hi:[1,0]
	v_pk_mul_f32 v[114:115], v[114:115], v[140:141] op_sel_hi:[1,0]
	v_pk_mul_f32 v[112:113], v[112:113], v[140:141] op_sel_hi:[1,0]
	v_pk_mul_f32 v[102:103], v[102:103], v[140:141] op_sel_hi:[1,0]
	v_pk_mul_f32 v[100:101], v[100:101], v[140:141] op_sel_hi:[1,0]
	v_pk_mul_f32 v[110:111], v[110:111], v[140:141] op_sel_hi:[1,0]
	v_pk_mul_f32 v[108:109], v[108:109], v[140:141] op_sel_hi:[1,0]
	v_pk_mul_f32 v[106:107], v[106:107], v[140:141] op_sel_hi:[1,0]
	v_pk_mul_f32 v[104:105], v[104:105], v[140:141] op_sel_hi:[1,0]
	v_mul_f32_e32 v183, v183, v140

.LBB0_422:
	v_mov_b32_e32 v132, v193
	v_mov_b32_e32 v133, v193
	s_nop 1
	v_permlane16_swap_b32_e32 v132, v133
	v_max_f32_e32 v132, v132, v133
	v_mov_b32_e32 v133, v132
	s_nop 1
	v_permlane32_swap_b32_e32 v132, v133
	v_max3_f32 v132, v240, v132, v133
	v_cmp_neq_f32_e32 vcc, v132, v240
	s_cbranch_vccz .LBB0_424
	v_sub_f32_e32 v133, v240, v132
	v_exp_f32_e32 v134, v133
	s_nop 0
	v_pk_mul_f32 v[98:99], v[98:99], v[134:135] op_sel_hi:[1,0]
	v_pk_mul_f32 v[96:97], v[96:97], v[134:135] op_sel_hi:[1,0]
	v_pk_mul_f32 v[94:95], v[94:95], v[134:135] op_sel_hi:[1,0]
	v_pk_mul_f32 v[92:93], v[92:93], v[134:135] op_sel_hi:[1,0]
	v_pk_mul_f32 v[90:91], v[90:91], v[134:135] op_sel_hi:[1,0]
	v_pk_mul_f32 v[88:89], v[88:89], v[134:135] op_sel_hi:[1,0]
	v_pk_mul_f32 v[86:87], v[86:87], v[134:135] op_sel_hi:[1,0]
	v_pk_mul_f32 v[84:85], v[84:85], v[134:135] op_sel_hi:[1,0]
	v_pk_mul_f32 v[82:83], v[82:83], v[134:135] op_sel_hi:[1,0]
	v_pk_mul_f32 v[80:81], v[80:81], v[134:135] op_sel_hi:[1,0]
	v_pk_mul_f32 v[70:71], v[70:71], v[134:135] op_sel_hi:[1,0]
	v_pk_mul_f32 v[68:69], v[68:69], v[134:135] op_sel_hi:[1,0]
	v_pk_mul_f32 v[78:79], v[78:79], v[134:135] op_sel_hi:[1,0]
	v_pk_mul_f32 v[76:77], v[76:77], v[134:135] op_sel_hi:[1,0]
	v_pk_mul_f32 v[74:75], v[74:75], v[134:135] op_sel_hi:[1,0]
	v_pk_mul_f32 v[72:73], v[72:73], v[134:135] op_sel_hi:[1,0]
	v_mul_f32_e32 v239, v239, v134

.LBB0_536:
	v_mov_b32_e32 v36, v59
	v_mov_b32_e32 v37, v59
	s_nop 1
	v_permlane16_swap_b32_e32 v36, v37
	v_max_f32_e32 v36, v36, v37
	v_mov_b32_e32 v37, v36
	s_nop 1
	v_permlane32_swap_b32_e32 v36, v37
	v_max3_f32 v36, v240, v36, v37
	v_cmp_neq_f32_e32 vcc, v36, v240
	s_cbranch_vccz .LBB0_538
	v_sub_f32_e32 v37, v240, v36
	v_exp_f32_e32 v38, v37
	s_nop 0
	v_pk_mul_f32 v[98:99], v[98:99], v[38:39] op_sel_hi:[1,0]
	v_pk_mul_f32 v[96:97], v[96:97], v[38:39] op_sel_hi:[1,0]
	v_pk_mul_f32 v[94:95], v[94:95], v[38:39] op_sel_hi:[1,0]
	v_pk_mul_f32 v[92:93], v[92:93], v[38:39] op_sel_hi:[1,0]
	v_pk_mul_f32 v[90:91], v[90:91], v[38:39] op_sel_hi:[1,0]
	v_pk_mul_f32 v[88:89], v[88:89], v[38:39] op_sel_hi:[1,0]
	v_pk_mul_f32 v[86:87], v[86:87], v[38:39] op_sel_hi:[1,0]
	v_pk_mul_f32 v[84:85], v[84:85], v[38:39] op_sel_hi:[1,0]
	v_pk_mul_f32 v[82:83], v[82:83], v[38:39] op_sel_hi:[1,0]
	v_pk_mul_f32 v[80:81], v[80:81], v[38:39] op_sel_hi:[1,0]
	v_pk_mul_f32 v[70:71], v[70:71], v[38:39] op_sel_hi:[1,0]
	v_pk_mul_f32 v[68:69], v[68:69], v[38:39] op_sel_hi:[1,0]
	v_pk_mul_f32 v[78:79], v[78:79], v[38:39] op_sel_hi:[1,0]
	v_pk_mul_f32 v[76:77], v[76:77], v[38:39] op_sel_hi:[1,0]
	v_pk_mul_f32 v[74:75], v[74:75], v[38:39] op_sel_hi:[1,0]
	v_pk_mul_f32 v[72:73], v[72:73], v[38:39] op_sel_hi:[1,0]
	v_mul_f32_e32 v239, v239, v38
